# P3: compression-MLP layer-2 GEMM rewritten by hand and spread over all 256 workgroups (was 32); plus P7 next-tile prefetch
# speedup vs baseline: 1.0225x; 1.0170x over previous
.LBB0_659:
	s_lshr_b32 s3, s2, 7
	s_and_b32 s4, s2, 0x7f
	v_readfirstlane_b32 s5, v238
	v_and_b32_e32 v2, 63, v238
	v_and_b32_e32 v3, 15, v238
	v_bfe_u32 v4, v238, 4, 2
	s_lshr_b32 s5, s5, 6
	s_and_b32 s6, s5, 1
	s_lshr_b32 s7, s5, 1
	s_lshl_b32 s22, s4, 5
	s_lshl_b32 s23, s6, 4
	s_add_i32 s22, s22, s23
	s_lshl_b32 s23, s3, 22
	s_lshl_b32 s24, s22, 10
	s_add_i32 s23, s23, s24
	s_lshl_b32 s24, s7, 8
	s_add_i32 s23, s23, s24
	s_add_u32 s8, s52, 0x192a0800
	s_addc_u32 s9, s53, 0
	s_add_u32 s8, s8, s23
	s_addc_u32 s9, s9, 0
	s_add_u32 s10, s8, 0x800000
	s_addc_u32 s11, s9, 0
	s_add_u32 s12, s8, 0x1000000
	s_addc_u32 s13, s9, 0
	s_add_u32 s14, s8, 0x1800000
	s_addc_u32 s15, s9, 0
	s_lshl_b32 s23, s3, 10
	s_add_i32 s23, s23, s24
	s_add_u32 s16, s52, 0x1a20000
	s_addc_u32 s17, s53, 0
	s_add_u32 s16, s16, s23
	s_addc_u32 s17, s17, 0
	s_lshl_b32 s23, s3, 16
	s_lshl_b32 s25, s7, 7
	s_add_i32 s23, s23, s25
	s_add_u32 s18, s52, 0x1a00000
	s_addc_u32 s19, s53, 0
	s_add_u32 s18, s18, s23
	s_addc_u32 s19, s19, 0
	v_lshlrev_b32_e32 v5, 10, v3
	v_lshl_add_u32 v5, v4, 5, v5
	v_lshlrev_b32_e32 v6, 5, v4
	v_lshlrev_b32_e32 v7, 9, v3
	v_lshl_add_u32 v7, v4, 4, v7
	v_add_u32_e32 v8, 0x2000, v7
	v_add_u32_e32 v9, 0x4000, v7
	v_add_u32_e32 v10, 0x6000, v7
	global_load_dwordx4 v[96:99], v7, s[18:19]
	global_load_dwordx4 v[100:103], v8, s[18:19]
	global_load_dwordx4 v[104:107], v9, s[18:19]
	global_load_dwordx4 v[108:111], v10, s[18:19]
	global_load_dwordx4 v[112:115], v7, s[18:19] offset:64
	global_load_dwordx4 v[116:119], v8, s[18:19] offset:64
	global_load_dwordx4 v[120:123], v9, s[18:19] offset:64
	global_load_dwordx4 v[124:127], v10, s[18:19] offset:64
	global_load_dwordx4 v[80:83], v6, s[16:17]
	global_load_dwordx4 v[84:87], v6, s[16:17] offset:16
	global_load_dwordx4 v[88:91], v6, s[16:17] offset:128
	global_load_dwordx4 v[92:95], v6, s[16:17] offset:144
	global_load_dwordx4 v[16:19], v5, s[8:9]
	global_load_dwordx4 v[20:23], v5, s[8:9] offset:16
	global_load_dwordx4 v[24:27], v5, s[10:11]
	global_load_dwordx4 v[28:31], v5, s[10:11] offset:16
	global_load_dwordx4 v[32:35], v5, s[12:13]
	global_load_dwordx4 v[36:39], v5, s[12:13] offset:16
	global_load_dwordx4 v[40:43], v5, s[14:15]
	global_load_dwordx4 v[44:47], v5, s[14:15] offset:16
	global_load_dwordx4 v[48:51], v5, s[8:9] offset:128
	global_load_dwordx4 v[52:55], v5, s[8:9] offset:144
	global_load_dwordx4 v[56:59], v5, s[10:11] offset:128
	global_load_dwordx4 v[60:63], v5, s[10:11] offset:144
	global_load_dwordx4 v[64:67], v5, s[12:13] offset:128
	global_load_dwordx4 v[68:71], v5, s[12:13] offset:144
	global_load_dwordx4 v[72:75], v5, s[14:15] offset:128
	global_load_dwordx4 v[76:79], v5, s[14:15] offset:144
	s_waitcnt vmcnt(0)
	v_add_f32_e32 v144, v16, v24
	v_add_f32_e32 v145, v17, v25
	v_add_f32_e32 v146, v18, v26
	v_add_f32_e32 v147, v19, v27
	v_add_f32_e32 v148, v20, v28
	v_add_f32_e32 v149, v21, v29
	v_add_f32_e32 v150, v22, v30
	v_add_f32_e32 v151, v23, v31
	v_add_f32_e32 v144, v144, v32
	v_add_f32_e32 v145, v145, v33
	v_add_f32_e32 v146, v146, v34
	v_add_f32_e32 v147, v147, v35
	v_add_f32_e32 v148, v148, v36
	v_add_f32_e32 v149, v149, v37
	v_add_f32_e32 v150, v150, v38
	v_add_f32_e32 v151, v151, v39
	v_add_f32_e32 v144, v144, v40
	v_add_f32_e32 v145, v145, v41
	v_add_f32_e32 v146, v146, v42
	v_add_f32_e32 v147, v147, v43
	v_add_f32_e32 v148, v148, v44
	v_add_f32_e32 v149, v149, v45
	v_add_f32_e32 v150, v150, v46
	v_add_f32_e32 v151, v151, v47
	v_add_f32_e32 v144, v144, v80
	v_add_f32_e32 v145, v145, v81
	v_add_f32_e32 v146, v146, v82
	v_add_f32_e32 v147, v147, v83
	v_add_f32_e32 v148, v148, v84
	v_add_f32_e32 v149, v149, v85
	v_add_f32_e32 v150, v150, v86
	v_add_f32_e32 v151, v151, v87
	v_mul_f32_e32 v160, 0xbfb8aa3b, v144
	v_mul_f32_e32 v161, 0xbfb8aa3b, v145
	v_mul_f32_e32 v162, 0xbfb8aa3b, v146
	v_mul_f32_e32 v163, 0xbfb8aa3b, v147
	v_mul_f32_e32 v164, 0xbfb8aa3b, v148
	v_mul_f32_e32 v165, 0xbfb8aa3b, v149
	v_mul_f32_e32 v166, 0xbfb8aa3b, v150
	v_mul_f32_e32 v167, 0xbfb8aa3b, v151
	v_exp_f32_e32 v160, v160
	v_exp_f32_e32 v161, v161
	v_exp_f32_e32 v162, v162
	v_exp_f32_e32 v163, v163
	v_exp_f32_e32 v164, v164
	v_exp_f32_e32 v165, v165
	v_exp_f32_e32 v166, v166
	v_exp_f32_e32 v167, v167
	v_add_f32_e32 v160, 1.0, v160
	v_add_f32_e32 v161, 1.0, v161
	v_add_f32_e32 v162, 1.0, v162
	v_add_f32_e32 v163, 1.0, v163
	v_add_f32_e32 v164, 1.0, v164
	v_add_f32_e32 v165, 1.0, v165
	v_add_f32_e32 v166, 1.0, v166
	v_add_f32_e32 v167, 1.0, v167
	v_rcp_f32_e32 v160, v160
	v_rcp_f32_e32 v161, v161
	v_rcp_f32_e32 v162, v162
	v_rcp_f32_e32 v163, v163
	v_rcp_f32_e32 v164, v164
	v_rcp_f32_e32 v165, v165
	v_rcp_f32_e32 v166, v166
	v_rcp_f32_e32 v167, v167
	v_mul_f32_e32 v144, v144, v160
	v_mul_f32_e32 v145, v145, v161
	v_mul_f32_e32 v146, v146, v162
	v_mul_f32_e32 v147, v147, v163
	v_mul_f32_e32 v148, v148, v164
	v_mul_f32_e32 v149, v149, v165
	v_mul_f32_e32 v150, v150, v166
	v_mul_f32_e32 v151, v151, v167
	v_cvt_pk_bf16_f32 v176, v144, v145
	v_cvt_pk_bf16_f32 v177, v146, v147
	v_cvt_pk_bf16_f32 v178, v148, v149
	v_cvt_pk_bf16_f32 v179, v150, v151
	v_add_f32_e32 v144, v48, v56
	v_add_f32_e32 v145, v49, v57
	v_add_f32_e32 v146, v50, v58
	v_add_f32_e32 v147, v51, v59
	v_add_f32_e32 v148, v52, v60
	v_add_f32_e32 v149, v53, v61
	v_add_f32_e32 v150, v54, v62
	v_add_f32_e32 v151, v55, v63
	v_add_f32_e32 v144, v144, v64
	v_add_f32_e32 v145, v145, v65
	v_add_f32_e32 v146, v146, v66
	v_add_f32_e32 v147, v147, v67
	v_add_f32_e32 v148, v148, v68
	v_add_f32_e32 v149, v149, v69
	v_add_f32_e32 v150, v150, v70
	v_add_f32_e32 v151, v151, v71
	v_add_f32_e32 v144, v144, v72
	v_add_f32_e32 v145, v145, v73
	v_add_f32_e32 v146, v146, v74
	v_add_f32_e32 v147, v147, v75
	v_add_f32_e32 v148, v148, v76
	v_add_f32_e32 v149, v149, v77
	v_add_f32_e32 v150, v150, v78
	v_add_f32_e32 v151, v151, v79
	v_add_f32_e32 v144, v144, v88
	v_add_f32_e32 v145, v145, v89
	v_add_f32_e32 v146, v146, v90
	v_add_f32_e32 v147, v147, v91
	v_add_f32_e32 v148, v148, v92
	v_add_f32_e32 v149, v149, v93
	v_add_f32_e32 v150, v150, v94
	v_add_f32_e32 v151, v151, v95
	v_mul_f32_e32 v160, 0xbfb8aa3b, v144
	v_mul_f32_e32 v161, 0xbfb8aa3b, v145
	v_mul_f32_e32 v162, 0xbfb8aa3b, v146
	v_mul_f32_e32 v163, 0xbfb8aa3b, v147
	v_mul_f32_e32 v164, 0xbfb8aa3b, v148
	v_mul_f32_e32 v165, 0xbfb8aa3b, v149
	v_mul_f32_e32 v166, 0xbfb8aa3b, v150
	v_mul_f32_e32 v167, 0xbfb8aa3b, v151
	v_exp_f32_e32 v160, v160
	v_exp_f32_e32 v161, v161
	v_exp_f32_e32 v162, v162
	v_exp_f32_e32 v163, v163
	v_exp_f32_e32 v164, v164
	v_exp_f32_e32 v165, v165
	v_exp_f32_e32 v166, v166
	v_exp_f32_e32 v167, v167
	v_add_f32_e32 v160, 1.0, v160
	v_add_f32_e32 v161, 1.0, v161
	v_add_f32_e32 v162, 1.0, v162
	v_add_f32_e32 v163, 1.0, v163
	v_add_f32_e32 v164, 1.0, v164
	v_add_f32_e32 v165, 1.0, v165
	v_add_f32_e32 v166, 1.0, v166
	v_add_f32_e32 v167, 1.0, v167
	v_rcp_f32_e32 v160, v160
	v_rcp_f32_e32 v161, v161
	v_rcp_f32_e32 v162, v162
	v_rcp_f32_e32 v163, v163
	v_rcp_f32_e32 v164, v164
	v_rcp_f32_e32 v165, v165
	v_rcp_f32_e32 v166, v166
	v_rcp_f32_e32 v167, v167
	v_mul_f32_e32 v144, v144, v160
	v_mul_f32_e32 v145, v145, v161
	v_mul_f32_e32 v146, v146, v162
	v_mul_f32_e32 v147, v147, v163
	v_mul_f32_e32 v148, v148, v164
	v_mul_f32_e32 v149, v149, v165
	v_mul_f32_e32 v150, v150, v166
	v_mul_f32_e32 v151, v151, v167
	v_cvt_pk_bf16_f32 v180, v144, v145
	v_cvt_pk_bf16_f32 v181, v146, v147
	v_cvt_pk_bf16_f32 v182, v148, v149
	v_cvt_pk_bf16_f32 v183, v150, v151
	s_nop 1
	v_mfma_f32_16x16x32_bf16 v[128:131], v[96:99], v[176:179], 0
	v_mfma_f32_16x16x32_bf16 v[132:135], v[100:103], v[176:179], 0
	v_mfma_f32_16x16x32_bf16 v[136:139], v[104:107], v[176:179], 0
	v_mfma_f32_16x16x32_bf16 v[140:143], v[108:111], v[176:179], 0
	v_mfma_f32_16x16x32_bf16 v[128:131], v[112:115], v[180:183], v[128:131]
	v_mfma_f32_16x16x32_bf16 v[132:135], v[116:119], v[180:183], v[132:135]
	v_mfma_f32_16x16x32_bf16 v[136:139], v[120:123], v[180:183], v[136:139]
	v_mfma_f32_16x16x32_bf16 v[140:143], v[124:127], v[180:183], v[140:143]
	s_lshl_b32 s23, s5, 12
	v_lshl_add_u32 v11, v2, 4, s23
	s_lshl_b32 s23, s6, 12
	s_lshl_b32 s24, s7, 10
	s_add_i32 s23, s23, s24
	v_lshl_add_u32 v12, v2, 4, s23
	s_nop 7
	s_nop 1
	ds_write_b128 v11, v[128:131]
	ds_write_b128 v11, v[132:135] offset:1024
	ds_write_b128 v11, v[136:139] offset:2048
	ds_write_b128 v11, v[140:143] offset:3072
	s_waitcnt lgkmcnt(0)
	s_barrier
	ds_read_b128 v[192:195], v12
	ds_read_b128 v[196:199], v12 offset:8192
	ds_read_b128 v[200:203], v12 offset:16384
	ds_read_b128 v[204:207], v12 offset:24576
	v_add_u32_e32 v13, s22, v3
	v_and_b32_e32 v14, 0x7f, v13
	v_cmp_ne_u32_e32 vcc, 0x7f, v14
	s_nop 1
	v_cndmask_b32_e64 v15, 0, 1.0, vcc
	s_waitcnt lgkmcnt(0)
	v_add_f32_e32 v192, v192, v196
	v_add_f32_e32 v193, v193, v197
	v_add_f32_e32 v194, v194, v198
	v_add_f32_e32 v195, v195, v199
	v_add_f32_e32 v192, v192, v200
	v_add_f32_e32 v193, v193, v201
	v_add_f32_e32 v194, v194, v202
	v_add_f32_e32 v195, v195, v203
	v_add_f32_e32 v192, v192, v204
	v_add_f32_e32 v193, v193, v205
	v_add_f32_e32 v194, v194, v206
	v_add_f32_e32 v195, v195, v207
	v_mul_f32_e32 v192, v192, v15
	v_mul_f32_e32 v193, v193, v15
	v_mul_f32_e32 v194, v194, v15
	v_mul_f32_e32 v195, v195, v15
	s_cmp_lg_u32 s3, 0
	s_cbranch_scc1 .Lc2x_v
	s_add_u32 s20, s52, 0x171a0800
	s_addc_u32 s21, s53, 0
	s_lshl_b32 s23, s7, 5
	v_lshlrev_b32_e32 v208, 7, v13
	v_lshl_add_u32 v208, v4, 3, v208
	v_add_u32_e32 v208, s23, v208
	v_cvt_pk_bf16_f32 v210, v192, v193
	v_cvt_pk_bf16_f32 v211, v194, v195
	s_nop 0
	global_store_dwordx2 v208, v[210:211], s[20:21]
	s_branch .Lc2x_done
.Lc2x_v:
	s_add_u32 s20, s52, 0x17220800
	s_addc_u32 s21, s53, 0
	s_lshl_b32 s23, s7, 12
	v_lshrrev_b32_e32 v208, 7, v13
	v_lshlrev_b32_e32 v208, 14, v208
	v_lshl_add_u32 v208, v14, 1, v208
	v_lshl_add_u32 v208, v4, 10, v208
	v_add_u32_e32 v208, s23, v208
	v_cvt_pk_bf16_f32 v210, v192, v192
	v_cvt_pk_bf16_f32 v211, v193, v193
	v_cvt_pk_bf16_f32 v212, v194, v194
	v_cvt_pk_bf16_f32 v213, v195, v195
	s_nop 0
	global_store_short v208, v210, s[20:21]
	global_store_short v208, v211, s[20:21] offset:256
	global_store_short v208, v212, s[20:21] offset:512
	global_store_short v208, v213, s[20:21] offset:768
.Lc2x_done:
.LBB0_691:
	s_waitcnt vmcnt(0)
	s_waitcnt vmcnt(63) expcnt(7) lgkmcnt(15)
	s_barrier
	s_mov_b64 s[66:67], exec
	v_readlane_b32 s4, v254, 1
	v_readlane_b32 s5, v254, 2
	s_and_b64 s[4:5], s[66:67], s[4:5]
	s_mov_b64 exec, s[4:5]
	s_cbranch_execz .LBB0_720
	s_waitcnt vmcnt(0) lgkmcnt(0)
	v_cmp_eq_u32_e32 vcc, 0, v240
	s_and_saveexec_b64 s[68:69], vcc
	s_cbranch_execz .LBB0_700
	s_add_u32 s70, s52, 0x1bfa0c00
	s_addc_u32 s71, s53, 0
	s_add_u32 s72, s52, 0x1bfa0d00
	s_addc_u32 s73, s53, 0
	s_add_u32 s74, s52, 0x1bfa0e00
	s_addc_u32 s75, s53, 0
	s_add_u32 s76, s52, 0x1bfa0f00
	s_addc_u32 s77, s53, 0
	s_add_u32 s78, s52, 0x1bfa1000
	s_addc_u32 s79, s53, 0
	s_add_u32 s80, s52, 0x1bfa1100
	s_addc_u32 s81, s53, 0
	s_add_u32 s82, s52, 0x1bfa1200
	s_addc_u32 s83, s53, 0
	s_add_u32 s84, s52, 0x1bfa1300
	s_addc_u32 s85, s53, 0
	s_add_u32 s86, s52, 0x1bfa1400
	s_addc_u32 s87, s53, 0
	s_add_u32 s88, s52, 0x1bfa1500
	s_addc_u32 s89, s53, 0
	s_add_u32 s90, s52, 0x1bfa1600
	s_addc_u32 s91, s53, 0
	s_add_u32 s92, s52, 0x1bfa1700
	s_addc_u32 s93, s53, 0
	s_add_u32 s94, s52, 0x1bfa1800
	s_addc_u32 s95, s53, 0
	s_add_u32 s4, s52, 0x1bfa1900
	s_addc_u32 s5, s53, 0
	s_add_u32 s42, s52, 0x1bfa1a00
	s_addc_u32 s43, s53, 0
	s_add_u32 s62, s52, 0x1bfa1b00
	s_addc_u32 s63, s53, 0
	v_readlane_b32 s3, v254, 0
	s_cmp_eq_u32 s3, 15
	s_cselect_b64 s[6:7], -1, 0
	s_cmp_eq_u32 s3, 14
	s_cselect_b64 s[8:9], -1, 0
	s_cmp_eq_u32 s3, 13
	s_cselect_b64 s[10:11], -1, 0
	s_cmp_eq_u32 s3, 12
	s_cselect_b64 s[12:13], -1, 0
	s_cmp_eq_u32 s3, 11
	s_cselect_b64 s[14:15], -1, 0
	s_cmp_eq_u32 s3, 10
	s_cselect_b64 s[16:17], -1, 0
	s_cmp_eq_u32 s3, 9
	s_cselect_b64 s[18:19], -1, 0
	s_cmp_eq_u32 s3, 8
	s_cselect_b64 s[20:21], -1, 0
	s_cmp_eq_u32 s3, 7
	s_cselect_b64 s[22:23], -1, 0
	s_cmp_eq_u32 s3, 6
	s_cselect_b64 s[24:25], -1, 0
	s_cmp_eq_u32 s3, 5
	s_cselect_b64 s[26:27], -1, 0
	s_cmp_eq_u32 s3, 4
	s_cselect_b64 s[28:29], -1, 0
	s_cmp_eq_u32 s3, 3
	s_cselect_b64 s[30:31], -1, 0
	s_cmp_eq_u32 s3, 2
	s_cselect_b64 s[34:35], -1, 0
	s_cmp_eq_u32 s3, 1
	s_cselect_b64 s[36:37], -1, 0
	s_cmp_eq_u32 s3, 0
	s_cselect_b64 s[38:39], -1, 0
	v_mov_b32_e32 v0, 0
	v_mov_b32_e32 v240, 0
	s_branch .LBB0_695
